# mixer A staging loads: row addresses via scalar group branch + v_med3 clamp + 32-bit offsets on SGPR bases (4 VALU per piece instead of 14)
# baseline (speedup 1.0000x reference)
; #define A_LOAD(SB) do { _Pragma("unroll") for (int it = 0; it < 6; ++it) { int pb, ki; A_GEOM(SB, it * 64 + srow, pb, ki); ki = ki < 0 ? 0 : (ki > L - 1 ? L - 1 : ki); \
;                 const size_t off = (size_t)(pb + ki) * 64 + sch * 8; kst[it] = *(const u32x4*)(Kg + off); vst[it] = *(const u32x4*)(Vg + off); } \
;             } while (0)
; __device__ __forceinline__ void attnA_unit(LAS unsigned char* lds, const Args& A, int unit) {
;     ...
;         for (int sb = 0; sb < nsb; ++sb) {
;             if (sb + 1 < nsb) A_LOAD(sb + 1);
.LBB0_288:
	s_add_i32 s97, s22, 1
	s_cmp_lt_u32 s97, s29
	s_cselect_b64 s[82:83], -1, 0
	s_cmp_ge_u32 s97, s29
	s_cbranch_scc1 .LBB0_290
	s_and_b64 s[24:25], s[76:77], exec
	s_cselect_b32 s23, 0, s97
	v_lshlrev_b32_e64 v4, v206, s23
	s_add_i32 s23, s90, 0x100
	s_and_b64 s[24:25], s[76:77], exec
	s_cselect_b32 s23, s23, s91
	v_add_u32_e32 v5, s23, v149
	s_cmp_lg_u64 s[20:21], 0
	s_cbranch_scc1 .LmixA_ld_g2
	v_med3_i32 v6, v5, 0, s28
	v_add_lshl_u32 v6, v6, v4, 7
	v_or_b32_e32 v6, v6, v154
	global_load_dwordx4 v[96:99], v6, s[44:45]
	global_load_dwordx4 v[100:103], v6, s[48:49]
	v_add_u32_e32 v7, s23, v147
	v_med3_i32 v7, v7, 0, s28
	v_add_lshl_u32 v7, v7, v4, 7
	v_or_b32_e32 v7, v7, v154
	global_load_dwordx4 v[104:107], v7, s[44:45]
	global_load_dwordx4 v[108:111], v7, s[48:49]
	v_add_u32_e32 v8, 0x80, v5
	v_med3_i32 v8, v8, 0, s28
	v_add_lshl_u32 v8, v8, v4, 7
	v_or_b32_e32 v8, v8, v154
	global_load_dwordx4 v[112:115], v8, s[44:45]
	global_load_dwordx4 v[116:119], v8, s[48:49]
	v_add_u32_e32 v9, 0xc0, v5
	v_med3_i32 v9, v9, 0, s28
	v_add_lshl_u32 v9, v9, v4, 7
	v_or_b32_e32 v9, v9, v154
	global_load_dwordx4 v[120:123], v9, s[44:45]
	global_load_dwordx4 v[124:127], v9, s[48:49]
	v_add_u32_e32 v10, 0x100, v5
	v_med3_i32 v10, v10, 0, s28
	v_add_lshl_u32 v10, v10, v4, 7
	v_or_b32_e32 v10, v10, v154
	global_load_dwordx4 v[128:131], v10, s[44:45]
	global_load_dwordx4 v[132:135], v10, s[48:49]
	v_add_u32_e32 v11, 0x140, v5
	v_med3_i32 v11, v11, 0, s28
	v_add_lshl_u32 v11, v11, v4, 7
	v_or_b32_e32 v11, v11, v154
	global_load_dwordx4 v[136:139], v11, s[44:45]
	global_load_dwordx4 v[140:143], v11, s[48:49]
	s_branch .LBB0_290
.LmixA_ld_g2:
	v_med3_i32 v6, v181, 0, s28
	v_add_lshl_u32 v12, v200, s96, v206
	v_add_lshl_u32 v6, v6, v12, 7
	v_or_b32_e32 v6, v6, v154
	global_load_dwordx4 v[96:99], v6, s[44:45]
	global_load_dwordx4 v[100:103], v6, s[48:49]
	v_med3_i32 v7, v182, 0, s28
	v_add_lshl_u32 v13, v199, s96, v206
	v_add_lshl_u32 v7, v7, v13, 7
	v_or_b32_e32 v7, v7, v154
	global_load_dwordx4 v[104:107], v7, s[44:45]
	global_load_dwordx4 v[108:111], v7, s[48:49]
	v_med3_i32 v8, v183, 0, s28
	v_add_lshl_u32 v14, v198, s96, v206
	v_add_lshl_u32 v8, v8, v14, 7
	v_or_b32_e32 v8, v8, v154
	global_load_dwordx4 v[112:115], v8, s[44:45]
	global_load_dwordx4 v[116:119], v8, s[48:49]
	v_med3_i32 v9, v190, 0, s28
	v_add_lshl_u32 v15, v197, s96, v206
	v_add_lshl_u32 v9, v9, v15, 7
	v_or_b32_e32 v9, v9, v154
	global_load_dwordx4 v[120:123], v9, s[44:45]
	global_load_dwordx4 v[124:127], v9, s[48:49]
	v_med3_i32 v10, v191, 0, s28
	v_add_lshl_u32 v16, v196, s96, v206
	v_add_lshl_u32 v10, v10, v16, 7
	v_or_b32_e32 v10, v10, v154
	global_load_dwordx4 v[128:131], v10, s[44:45]
	global_load_dwordx4 v[132:135], v10, s[48:49]
	v_med3_i32 v11, v192, 0, s28
	v_add_lshl_u32 v17, v195, s96, v206
	v_add_lshl_u32 v11, v11, v17, 7
	v_or_b32_e32 v11, v11, v154
	global_load_dwordx4 v[136:139], v11, s[44:45]
	global_load_dwordx4 v[140:143], v11, s[48:49]
